# input-projection (P1) epilogue stores (u, v, new_conv rows; consumed on other XCDs after the next barrier) carry the nt hint
# speedup vs baseline: 1.0030x; 1.0030x over previous
; #define LAS __attribute__((address_space(3)))
; __device__ __forceinline__ float sigmoidf_(float x) { return __builtin_amdgcn_rcpf(1.f + __builtin_amdgcn_exp2f(-1.4426950408889634f * x)); }
; #define EPI_FOR_ROWS for (int ai = 0; ai < 2; ++ai) _Pragma("unroll") for (int m = 0; m < 4; ++m)
; __device__ __forceinline__ u32x4 pack8(const f32x4 a, const f32x4 b) { u32x4 w; w.x = cvt_pk_bf16(a[0], a[1]); w.y = cvt_pk_bf16(a[2], a[3]); w.z = cvt_pk_bf16(b[0], b[1]); w.w = cvt_pk_bf16(b[2], b[3]); return w; }
;     __device__ __forceinline__ void conv_piece(size_t row, int ch, f32x4 v0, f32x4 v1, const f32x4 g0, const f32x4 g1) const {
; #pragma unroll
;         for (int e = 0; e < 4; ++e) { v0[e] *= sigmoidf_(g0[e]); v1[e] *= sigmoidf_(g1[e]); }
;         *(u32x4*)(Vb + row * DCONV + ch) = pack8(v0, v1);
;         float* dst = nullptr;
;         if (row >= (size_t)NP) { const int r = (int)row - NP; dst = out + O_CVS + (size_t)((r >> 4) * 30 + 14 + (r & 15)) * DCONV + ch; }
;         else { const int t = (int)row & (SEQ - 1); if (t >= SEQ - 30) dst = out + O_CVP + (size_t)(((int)row >> 14) * 30 + (t - (SEQ - 30))) * DCONV + ch; }
;         if (dst) { *(f32x4*)dst = v0; *(f32x4*)(dst + 4) = v1; }
;     }
;     __device__ __forceinline__ void small(size_t row, int col, const f32x4 v0, const f32x4 v1) const { *(u32x4*)(Ub + row * DSSM + col) = pack8(v0, v1); }
;     __device__ __forceinline__ void operator()(const f32x4 (&acc)[2][2][4][2], const Unit& u, int wr, int wc, int fr_, int fq_, LAS unsigned char*) const {
;         int fr = fr_, fq = fq_; asm volatile("" : "+v"(fr), "+v"(fq));
;         const int pn = u.aux;
; #pragma unroll
;         EPI_FOR_ROWS {
;             const int rl = ai * HALF + wr * 64 + m * 16 + fr; const size_t row = (size_t)u.row0 + rl;
;             if (pn < 2) {
; #pragma unroll
;                 for (int bj = 0; bj < 2; ++bj) *(u32x4*)(Ub + row * DSSM + pn * 256 + bj * HALF + wc * 32 + 8 * fq) = pack8(acc[ai][bj][m][0], acc[ai][bj][m][1]);
;             } else {
;                 conv_piece(row, (pn - 2) * 128 + wc * 32 + 8 * fq, acc[ai][0][m][0], acc[ai][0][m][1], acc[ai][1][m][0], acc[ai][1][m][1]);
.LBB0_331:
	s_ashr_i32 s17, s16, 31
	v_mov_b32_e32 v128, v166
	v_mov_b32_e32 v129, v167
	s_cmp_gt_i32 s10, 1
	s_cselect_b64 s[28:29], -1, 0
	v_add_u32_e32 v158, s70, v128
	s_lshl_b32 s4, s10, 7
	v_lshlrev_b32_e32 v154, 3, v129
	s_add_i32 s4, s75, s4
	v_ashrrev_i32_e32 v159, 31, v158
	v_add_u32_e32 v156, s4, v154
	v_lshl_add_u64 v[162:163], v[158:159], 0, s[16:17]
	v_ashrrev_i32_e32 v157, 31, v156
	s_mov_b64 s[4:5], -1
	s_and_b64 vcc, exec, s[28:29]
	v_lshlrev_b64 v[160:161], 10, v[162:163]
	s_cbranch_vccz .LBB0_339
	v_mul_f32_e32 v129, 0xbfb8aa3b, v112
	v_mul_f32_e32 v130, 0xbfb8aa3b, v117
	v_exp_f32_e32 v129, v129
	v_exp_f32_e32 v131, v130
	v_mul_f32_e32 v130, 0xbfb8aa3b, v113
	v_exp_f32_e32 v132, v130
	v_add_f32_e32 v129, 1.0, v129
	v_rcp_f32_e32 v130, v129
	v_add_f32_e32 v129, 1.0, v131
	v_add_f32_e32 v131, 1.0, v132
	v_mul_f32_e32 v132, 0xbfb8aa3b, v118
	v_exp_f32_e32 v132, v132
	v_mul_f32_e32 v133, 0xbfb8aa3b, v114
	v_exp_f32_e32 v133, v133
	v_mul_f32_e32 v128, 0xbfb8aa3b, v116
	v_add_f32_e32 v132, 1.0, v132
	v_rcp_f32_e32 v134, v132
	v_add_f32_e32 v132, 1.0, v133
	v_mul_f32_e32 v133, 0xbfb8aa3b, v119
	v_exp_f32_e32 v133, v133
	v_mul_f32_e32 v135, 0xbfb8aa3b, v115
	v_exp_f32_e32 v128, v128
	v_exp_f32_e32 v144, v135
	v_rcp_f32_e32 v164, v132
	v_add_f32_e32 v132, 1.0, v133
	v_add_f32_e32 v128, 1.0, v128
	v_rcp_f32_e32 v135, v132
	v_add_f32_e32 v132, 1.0, v144
	v_rcp_f32_e32 v128, v128
	v_rcp_f32_e32 v129, v129
	v_rcp_f32_e32 v131, v131
	v_rcp_f32_e32 v165, v132
	v_pk_mul_f32 v[134:135], v[126:127], v[134:135]
	v_pk_mul_f32 v[132:133], v[124:125], v[128:129]
	v_pk_mul_f32 v[128:129], v[120:121], v[130:131]
	v_pk_mul_f32 v[130:131], v[122:123], v[164:165]
	v_lshl_add_u64 v[164:165], s[36:37], 0, v[160:161]
	v_lshl_add_u64 v[164:165], v[156:157], 1, v[164:165]
	v_cmp_gt_u64_e32 vcc, s[20:21], v[162:163]
	v_cvt_pk_bf16_f32 v172, v132, v133
	v_cvt_pk_bf16_f32 v173, v134, v135
	v_cvt_pk_bf16_f32 v174, v128, v129
	v_cvt_pk_bf16_f32 v175, v130, v131
	global_store_dwordx4 v[164:165], v[172:175], off nt
	s_and_saveexec_b64 s[4:5], vcc
	s_xor_b64 s[4:5], exec, s[4:5]
	s_cbranch_execz .LBB0_414
	v_and_b32_e32 v144, 0x3fff, v162
	v_cmp_lt_u32_e32 vcc, s78, v144
	v_mov_b64_e32 v[164:165], 0
	s_and_saveexec_b64 s[26:27], vcc
	v_lshrrev_b32_e32 v155, 14, v162
	v_mul_u32_u24_e32 v155, 30, v155
	v_add3_u32 v144, v144, v155, s79
	v_lshlrev_b64 v[162:163], 11, v[144:145]
	v_lshl_add_u64 v[162:163], s[6:7], 0, v[162:163]
	v_lshl_add_u64 v[164:165], v[156:157], 2, v[162:163]
	s_or_b64 exec, exec, s[26:27]
	s_andn2_saveexec_b64 s[4:5], s[4:5]
	s_cbranch_execnz .LBB0_415

;     __device__ __forceinline__ void conv_piece(size_t row, int ch, f32x4 v0, f32x4 v1, const f32x4 g0, const f32x4 g1) const {
;     ...
;         if (dst) { *(f32x4*)dst = v0; *(f32x4*)(dst + 4) = v1; }
.LBB0_337:
	global_store_dwordx4 v[164:165], v[132:135], off nt
	global_store_dwordx4 v[164:165], v[128:131], off offset:16 nt

; #define LAS __attribute__((address_space(3)))
; __device__ __forceinline__ float sigmoidf_(float x) { return __builtin_amdgcn_rcpf(1.f + __builtin_amdgcn_exp2f(-1.4426950408889634f * x)); }
; #define EPI_FOR_ROWS for (int ai = 0; ai < 2; ++ai) _Pragma("unroll") for (int m = 0; m < 4; ++m)
; __device__ __forceinline__ u32x4 pack8(const f32x4 a, const f32x4 b) { u32x4 w; w.x = cvt_pk_bf16(a[0], a[1]); w.y = cvt_pk_bf16(a[2], a[3]); w.z = cvt_pk_bf16(b[0], b[1]); w.w = cvt_pk_bf16(b[2], b[3]); return w; }
;     __device__ __forceinline__ void conv_piece(size_t row, int ch, f32x4 v0, f32x4 v1, const f32x4 g0, const f32x4 g1) const {
; #pragma unroll
;         for (int e = 0; e < 4; ++e) { v0[e] *= sigmoidf_(g0[e]); v1[e] *= sigmoidf_(g1[e]); }
;         *(u32x4*)(Vb + row * DCONV + ch) = pack8(v0, v1);
;         float* dst = nullptr;
;         if (row >= (size_t)NP) { const int r = (int)row - NP; dst = out + O_CVS + (size_t)((r >> 4) * 30 + 14 + (r & 15)) * DCONV + ch; }
;         else { const int t = (int)row & (SEQ - 1); if (t >= SEQ - 30) dst = out + O_CVP + (size_t)(((int)row >> 14) * 30 + (t - (SEQ - 30))) * DCONV + ch; }
;         if (dst) { *(f32x4*)dst = v0; *(f32x4*)(dst + 4) = v1; }
;     }
;     __device__ __forceinline__ void small(size_t row, int col, const f32x4 v0, const f32x4 v1) const { *(u32x4*)(Ub + row * DSSM + col) = pack8(v0, v1); }
;     __device__ __forceinline__ void operator()(const f32x4 (&acc)[2][2][4][2], const Unit& u, int wr, int wc, int fr_, int fq_, LAS unsigned char*) const {
;         int fr = fr_, fq = fq_; asm volatile("" : "+v"(fr), "+v"(fq));
;         const int pn = u.aux;
; #pragma unroll
;         EPI_FOR_ROWS {
;             const int rl = ai * HALF + wr * 64 + m * 16 + fr; const size_t row = (size_t)u.row0 + rl;
;             if (pn < 2) {
; #pragma unroll
;                 for (int bj = 0; bj < 2; ++bj) *(u32x4*)(Ub + row * DSSM + pn * 256 + bj * HALF + wc * 32 + 8 * fq) = pack8(acc[ai][bj][m][0], acc[ai][bj][m][1]);
;             } else {
;                 conv_piece(row, (pn - 2) * 128 + wc * 32 + 8 * fq, acc[ai][0][m][0], acc[ai][0][m][1], acc[ai][1][m][0], acc[ai][1][m][1]);
.LBB0_339:
	s_lshl_b32 s62, s10, 8
	s_ashr_i32 s63, s62, 31
	v_ashrrev_i32_e32 v155, 31, v154
	s_and_b64 vcc, exec, s[4:5]
	s_cbranch_vccz .LBB0_341
	v_cvt_pk_bf16_f32 v124, v124, v125
	v_cvt_pk_bf16_f32 v125, v126, v127
	v_cvt_pk_bf16_f32 v126, v120, v121
	v_lshl_add_u64 v[120:121], s[60:61], 0, v[160:161]
	v_lshl_add_u64 v[120:121], s[62:63], 1, v[120:121]
	s_lshl_b32 s10, s71, 1
	v_lshl_add_u64 v[120:121], v[120:121], 0, s[10:11]
	v_lshl_add_u64 v[120:121], v[154:155], 1, v[120:121]
	v_cvt_pk_bf16_f32 v127, v122, v123
	global_store_dwordx4 v[120:121], v[124:127], off nt
	v_cvt_pk_bf16_f32 v116, v116, v117
	v_cvt_pk_bf16_f32 v117, v118, v119
	v_cvt_pk_bf16_f32 v118, v112, v113
	v_cvt_pk_bf16_f32 v119, v114, v115
	global_store_dwordx4 v[120:121], v[116:119], off offset:256 nt
.LBB0_341:
	v_add_u32_e32 v112, 16, v158
	v_ashrrev_i32_e32 v113, 31, v112
	v_lshl_add_u64 v[122:123], v[112:113], 0, s[16:17]
	v_cndmask_b32_e64 v112, 0, 1, s[28:29]
	s_mov_b64 s[26:27], -1
	v_cmp_ne_u32_e64 s[4:5], 1, v112
	s_andn2_b64 vcc, exec, s[28:29]
	v_lshlrev_b64 v[120:121], 10, v[122:123]
	s_cbranch_vccnz .LBB0_349
	v_mul_f32_e32 v113, 0xbfb8aa3b, v96
	v_mul_f32_e32 v114, 0xbfb8aa3b, v101
	v_exp_f32_e32 v113, v113
	v_exp_f32_e32 v115, v114
	v_mul_f32_e32 v114, 0xbfb8aa3b, v97
	v_exp_f32_e32 v116, v114
	v_add_f32_e32 v113, 1.0, v113
	v_rcp_f32_e32 v114, v113
	v_add_f32_e32 v113, 1.0, v115
	v_add_f32_e32 v115, 1.0, v116
	v_mul_f32_e32 v116, 0xbfb8aa3b, v102
	v_exp_f32_e32 v116, v116
	v_mul_f32_e32 v117, 0xbfb8aa3b, v98
	v_exp_f32_e32 v117, v117
	v_mul_f32_e32 v112, 0xbfb8aa3b, v100
	v_add_f32_e32 v116, 1.0, v116
	v_rcp_f32_e32 v118, v116
	v_add_f32_e32 v116, 1.0, v117
	v_mul_f32_e32 v117, 0xbfb8aa3b, v103
	v_exp_f32_e32 v117, v117
	v_mul_f32_e32 v119, 0xbfb8aa3b, v99
	v_exp_f32_e32 v112, v112
	v_exp_f32_e32 v125, v119
	v_rcp_f32_e32 v124, v116
	v_add_f32_e32 v116, 1.0, v117
	v_add_f32_e32 v112, 1.0, v112
	v_rcp_f32_e32 v119, v116
	v_add_f32_e32 v116, 1.0, v125
	v_rcp_f32_e32 v112, v112
	v_rcp_f32_e32 v113, v113
	v_rcp_f32_e32 v115, v115
	v_rcp_f32_e32 v125, v116
	v_lshl_add_u64 v[128:129], s[36:37], 0, v[120:121]
	v_pk_mul_f32 v[116:117], v[108:109], v[112:113]
	v_pk_mul_f32 v[112:113], v[104:105], v[114:115]
	v_pk_mul_f32 v[118:119], v[110:111], v[118:119]
	v_pk_mul_f32 v[114:115], v[106:107], v[124:125]
	v_cvt_pk_bf16_f32 v124, v116, v117
	v_cvt_pk_bf16_f32 v125, v118, v119
	v_lshl_add_u64 v[128:129], v[156:157], 1, v[128:129]
	v_cmp_gt_u64_e32 vcc, s[20:21], v[122:123]
	v_cvt_pk_bf16_f32 v126, v112, v113
	v_cvt_pk_bf16_f32 v127, v114, v115
	global_store_dwordx4 v[128:129], v[124:127], off nt
	s_and_saveexec_b64 s[26:27], vcc
	s_xor_b64 s[26:27], exec, s[26:27]
	s_cbranch_execz .LBB0_416
	v_and_b32_e32 v123, 0x3fff, v122
	v_cmp_lt_u32_e32 vcc, s78, v123
	v_mov_b64_e32 v[124:125], 0
	s_and_saveexec_b64 s[28:29], vcc
	v_lshrrev_b32_e32 v122, 14, v122
	v_mul_u32_u24_e32 v122, 30, v122
	v_add3_u32 v144, v123, v122, s79
	v_lshlrev_b64 v[122:123], 11, v[144:145]
	v_lshl_add_u64 v[122:123], s[6:7], 0, v[122:123]
	v_lshl_add_u64 v[124:125], v[156:157], 2, v[122:123]
	s_or_b64 exec, exec, s[28:29]
	s_andn2_saveexec_b64 s[26:27], s[26:27]
	s_cbranch_execnz .LBB0_417

;     __device__ __forceinline__ void conv_piece(size_t row, int ch, f32x4 v0, f32x4 v1, const f32x4 g0, const f32x4 g1) const {
;     ...
;         if (dst) { *(f32x4*)dst = v0; *(f32x4*)(dst + 4) = v1; }
.LBB0_347:
	global_store_dwordx4 v[124:125], v[116:119], off nt
	global_store_dwordx4 v[124:125], v[112:115], off offset:16 nt

; #define LAS __attribute__((address_space(3)))
; __device__ __forceinline__ float sigmoidf_(float x) { return __builtin_amdgcn_rcpf(1.f + __builtin_amdgcn_exp2f(-1.4426950408889634f * x)); }
; #define EPI_FOR_ROWS for (int ai = 0; ai < 2; ++ai) _Pragma("unroll") for (int m = 0; m < 4; ++m)
; __device__ __forceinline__ u32x4 pack8(const f32x4 a, const f32x4 b) { u32x4 w; w.x = cvt_pk_bf16(a[0], a[1]); w.y = cvt_pk_bf16(a[2], a[3]); w.z = cvt_pk_bf16(b[0], b[1]); w.w = cvt_pk_bf16(b[2], b[3]); return w; }
;     __device__ __forceinline__ void conv_piece(size_t row, int ch, f32x4 v0, f32x4 v1, const f32x4 g0, const f32x4 g1) const {
; #pragma unroll
;         for (int e = 0; e < 4; ++e) { v0[e] *= sigmoidf_(g0[e]); v1[e] *= sigmoidf_(g1[e]); }
;         *(u32x4*)(Vb + row * DCONV + ch) = pack8(v0, v1);
;         float* dst = nullptr;
;         if (row >= (size_t)NP) { const int r = (int)row - NP; dst = out + O_CVS + (size_t)((r >> 4) * 30 + 14 + (r & 15)) * DCONV + ch; }
;         else { const int t = (int)row & (SEQ - 1); if (t >= SEQ - 30) dst = out + O_CVP + (size_t)(((int)row >> 14) * 30 + (t - (SEQ - 30))) * DCONV + ch; }
;         if (dst) { *(f32x4*)dst = v0; *(f32x4*)(dst + 4) = v1; }
;     }
;     __device__ __forceinline__ void small(size_t row, int col, const f32x4 v0, const f32x4 v1) const { *(u32x4*)(Ub + row * DSSM + col) = pack8(v0, v1); }
;     __device__ __forceinline__ void operator()(const f32x4 (&acc)[2][2][4][2], const Unit& u, int wr, int wc, int fr_, int fq_, LAS unsigned char*) const {
;         int fr = fr_, fq = fq_; asm volatile("" : "+v"(fr), "+v"(fq));
;         const int pn = u.aux;
; #pragma unroll
;         EPI_FOR_ROWS {
;             const int rl = ai * HALF + wr * 64 + m * 16 + fr; const size_t row = (size_t)u.row0 + rl;
;             if (pn < 2) {
; #pragma unroll
;                 for (int bj = 0; bj < 2; ++bj) *(u32x4*)(Ub + row * DSSM + pn * 256 + bj * HALF + wc * 32 + 8 * fq) = pack8(acc[ai][bj][m][0], acc[ai][bj][m][1]);
;             } else {
;                 conv_piece(row, (pn - 2) * 128 + wc * 32 + 8 * fq, acc[ai][0][m][0], acc[ai][0][m][1], acc[ai][1][m][0], acc[ai][1][m][1]);
.LBB0_349:
	s_and_b64 vcc, exec, s[26:27]
	s_cbranch_vccz .LBB0_351
	v_cvt_pk_bf16_f32 v108, v108, v109
	v_cvt_pk_bf16_f32 v109, v110, v111
	v_cvt_pk_bf16_f32 v110, v104, v105
	v_lshl_add_u64 v[104:105], s[60:61], 0, v[120:121]
	v_lshl_add_u64 v[104:105], s[62:63], 1, v[104:105]
	s_lshl_b32 s10, s71, 1
	v_lshl_add_u64 v[104:105], v[104:105], 0, s[10:11]
	v_lshl_add_u64 v[104:105], v[154:155], 1, v[104:105]
	v_cvt_pk_bf16_f32 v111, v106, v107
	global_store_dwordx4 v[104:105], v[108:111], off nt
	v_cvt_pk_bf16_f32 v100, v100, v101
	v_cvt_pk_bf16_f32 v101, v102, v103
	v_cvt_pk_bf16_f32 v102, v96, v97
	v_cvt_pk_bf16_f32 v103, v98, v99
	global_store_dwordx4 v[104:105], v[100:103], off offset:256 nt
.LBB0_351:
	v_add_u32_e32 v96, 32, v158
	v_ashrrev_i32_e32 v97, 31, v96
	v_lshl_add_u64 v[106:107], v[96:97], 0, s[16:17]
	s_mov_b64 s[26:27], -1
	s_and_b64 vcc, exec, s[4:5]
	v_lshlrev_b64 v[104:105], 10, v[106:107]
	s_cbranch_vccnz .LBB0_359
	v_mul_f32_e32 v97, 0xbfb8aa3b, v80
	v_mul_f32_e32 v98, 0xbfb8aa3b, v85
	v_exp_f32_e32 v97, v97
	v_exp_f32_e32 v99, v98
	v_mul_f32_e32 v98, 0xbfb8aa3b, v81
	v_exp_f32_e32 v100, v98
	v_add_f32_e32 v97, 1.0, v97
	v_rcp_f32_e32 v98, v97
	v_add_f32_e32 v97, 1.0, v99
	v_add_f32_e32 v99, 1.0, v100
	v_mul_f32_e32 v100, 0xbfb8aa3b, v86
	v_exp_f32_e32 v100, v100
	v_mul_f32_e32 v101, 0xbfb8aa3b, v82
	v_exp_f32_e32 v101, v101
	v_mul_f32_e32 v96, 0xbfb8aa3b, v84
	v_add_f32_e32 v100, 1.0, v100
	v_rcp_f32_e32 v102, v100
	v_add_f32_e32 v100, 1.0, v101
	v_mul_f32_e32 v101, 0xbfb8aa3b, v87
	v_exp_f32_e32 v101, v101
	v_mul_f32_e32 v103, 0xbfb8aa3b, v83
	v_exp_f32_e32 v96, v96
	v_exp_f32_e32 v109, v103
	v_rcp_f32_e32 v108, v100
	v_add_f32_e32 v100, 1.0, v101
	v_add_f32_e32 v96, 1.0, v96
	v_rcp_f32_e32 v103, v100
	v_add_f32_e32 v100, 1.0, v109
	v_rcp_f32_e32 v96, v96
	v_rcp_f32_e32 v97, v97
	v_rcp_f32_e32 v99, v99
	v_rcp_f32_e32 v109, v100
	v_lshl_add_u64 v[112:113], s[36:37], 0, v[104:105]
	v_pk_mul_f32 v[100:101], v[92:93], v[96:97]
	v_pk_mul_f32 v[96:97], v[88:89], v[98:99]
	v_pk_mul_f32 v[102:103], v[94:95], v[102:103]
	v_pk_mul_f32 v[98:99], v[90:91], v[108:109]
	v_cvt_pk_bf16_f32 v108, v100, v101
	v_cvt_pk_bf16_f32 v109, v102, v103
	v_lshl_add_u64 v[112:113], v[156:157], 1, v[112:113]
	v_cmp_gt_u64_e32 vcc, s[20:21], v[106:107]
	v_cvt_pk_bf16_f32 v110, v96, v97
	v_cvt_pk_bf16_f32 v111, v98, v99
	global_store_dwordx4 v[112:113], v[108:111], off nt
	s_and_saveexec_b64 s[26:27], vcc
	s_xor_b64 s[26:27], exec, s[26:27]
	s_cbranch_execz .LBB0_418
	v_and_b32_e32 v107, 0x3fff, v106
	v_cmp_lt_u32_e32 vcc, s78, v107
	v_mov_b64_e32 v[108:109], 0
	s_and_saveexec_b64 s[28:29], vcc
	v_lshrrev_b32_e32 v106, 14, v106
	v_mul_u32_u24_e32 v106, 30, v106
	v_add3_u32 v144, v107, v106, s79
	v_lshlrev_b64 v[106:107], 11, v[144:145]
	v_lshl_add_u64 v[106:107], s[6:7], 0, v[106:107]
	v_lshl_add_u64 v[108:109], v[156:157], 2, v[106:107]
	s_or_b64 exec, exec, s[28:29]
	s_andn2_saveexec_b64 s[26:27], s[26:27]
	s_cbranch_execnz .LBB0_419

;     __device__ __forceinline__ void conv_piece(size_t row, int ch, f32x4 v0, f32x4 v1, const f32x4 g0, const f32x4 g1) const {
;     ...
;         if (dst) { *(f32x4*)dst = v0; *(f32x4*)(dst + 4) = v1; }
.LBB0_357:
	global_store_dwordx4 v[108:109], v[100:103], off nt
	global_store_dwordx4 v[108:109], v[96:99], off offset:16 nt

; #define LAS __attribute__((address_space(3)))
; __device__ __forceinline__ float sigmoidf_(float x) { return __builtin_amdgcn_rcpf(1.f + __builtin_amdgcn_exp2f(-1.4426950408889634f * x)); }
; #define EPI_FOR_ROWS for (int ai = 0; ai < 2; ++ai) _Pragma("unroll") for (int m = 0; m < 4; ++m)
; __device__ __forceinline__ u32x4 pack8(const f32x4 a, const f32x4 b) { u32x4 w; w.x = cvt_pk_bf16(a[0], a[1]); w.y = cvt_pk_bf16(a[2], a[3]); w.z = cvt_pk_bf16(b[0], b[1]); w.w = cvt_pk_bf16(b[2], b[3]); return w; }
;     __device__ __forceinline__ void conv_piece(size_t row, int ch, f32x4 v0, f32x4 v1, const f32x4 g0, const f32x4 g1) const {
; #pragma unroll
;         for (int e = 0; e < 4; ++e) { v0[e] *= sigmoidf_(g0[e]); v1[e] *= sigmoidf_(g1[e]); }
;         *(u32x4*)(Vb + row * DCONV + ch) = pack8(v0, v1);
;         float* dst = nullptr;
;         if (row >= (size_t)NP) { const int r = (int)row - NP; dst = out + O_CVS + (size_t)((r >> 4) * 30 + 14 + (r & 15)) * DCONV + ch; }
;         else { const int t = (int)row & (SEQ - 1); if (t >= SEQ - 30) dst = out + O_CVP + (size_t)(((int)row >> 14) * 30 + (t - (SEQ - 30))) * DCONV + ch; }
;         if (dst) { *(f32x4*)dst = v0; *(f32x4*)(dst + 4) = v1; }
;     }
;     __device__ __forceinline__ void small(size_t row, int col, const f32x4 v0, const f32x4 v1) const { *(u32x4*)(Ub + row * DSSM + col) = pack8(v0, v1); }
;     __device__ __forceinline__ void operator()(const f32x4 (&acc)[2][2][4][2], const Unit& u, int wr, int wc, int fr_, int fq_, LAS unsigned char*) const {
;         int fr = fr_, fq = fq_; asm volatile("" : "+v"(fr), "+v"(fq));
;         const int pn = u.aux;
; #pragma unroll
;         EPI_FOR_ROWS {
;             const int rl = ai * HALF + wr * 64 + m * 16 + fr; const size_t row = (size_t)u.row0 + rl;
;             if (pn < 2) {
; #pragma unroll
;                 for (int bj = 0; bj < 2; ++bj) *(u32x4*)(Ub + row * DSSM + pn * 256 + bj * HALF + wc * 32 + 8 * fq) = pack8(acc[ai][bj][m][0], acc[ai][bj][m][1]);
;             } else {
;                 conv_piece(row, (pn - 2) * 128 + wc * 32 + 8 * fq, acc[ai][0][m][0], acc[ai][0][m][1], acc[ai][1][m][0], acc[ai][1][m][1]);
.LBB0_359:
	s_and_b64 vcc, exec, s[26:27]
	s_cbranch_vccz .LBB0_361
	v_cvt_pk_bf16_f32 v92, v92, v93
	v_cvt_pk_bf16_f32 v93, v94, v95
	v_cvt_pk_bf16_f32 v94, v88, v89
	v_lshl_add_u64 v[88:89], s[60:61], 0, v[104:105]
	v_lshl_add_u64 v[88:89], s[62:63], 1, v[88:89]
	s_lshl_b32 s10, s71, 1
	v_lshl_add_u64 v[88:89], v[88:89], 0, s[10:11]
	v_lshl_add_u64 v[88:89], v[154:155], 1, v[88:89]
	v_cvt_pk_bf16_f32 v95, v90, v91
	global_store_dwordx4 v[88:89], v[92:95], off nt
	v_cvt_pk_bf16_f32 v84, v84, v85
	v_cvt_pk_bf16_f32 v85, v86, v87
	v_cvt_pk_bf16_f32 v86, v80, v81
	v_cvt_pk_bf16_f32 v87, v82, v83
	global_store_dwordx4 v[88:89], v[84:87], off offset:256 nt
.LBB0_361:
	v_add_u32_e32 v80, 48, v158
	v_ashrrev_i32_e32 v81, 31, v80
	v_lshl_add_u64 v[90:91], v[80:81], 0, s[16:17]
	s_mov_b64 s[26:27], -1
	s_and_b64 vcc, exec, s[4:5]
	v_lshlrev_b64 v[88:89], 10, v[90:91]
	s_cbranch_vccnz .LBB0_369
	v_mul_f32_e32 v81, 0xbfb8aa3b, v64
	v_mul_f32_e32 v82, 0xbfb8aa3b, v69
	v_exp_f32_e32 v81, v81
	v_exp_f32_e32 v83, v82
	v_mul_f32_e32 v82, 0xbfb8aa3b, v65
	v_exp_f32_e32 v84, v82
	v_add_f32_e32 v81, 1.0, v81
	v_rcp_f32_e32 v82, v81
	v_add_f32_e32 v81, 1.0, v83
	v_add_f32_e32 v83, 1.0, v84
	v_mul_f32_e32 v84, 0xbfb8aa3b, v70
	v_exp_f32_e32 v84, v84
	v_mul_f32_e32 v85, 0xbfb8aa3b, v66
	v_exp_f32_e32 v85, v85
	v_mul_f32_e32 v80, 0xbfb8aa3b, v68
	v_add_f32_e32 v84, 1.0, v84
	v_rcp_f32_e32 v86, v84
	v_add_f32_e32 v84, 1.0, v85
	v_mul_f32_e32 v85, 0xbfb8aa3b, v71
	v_exp_f32_e32 v85, v85
	v_mul_f32_e32 v87, 0xbfb8aa3b, v67
	v_exp_f32_e32 v80, v80
	v_exp_f32_e32 v93, v87
	v_rcp_f32_e32 v92, v84
	v_add_f32_e32 v84, 1.0, v85
	v_add_f32_e32 v80, 1.0, v80
	v_rcp_f32_e32 v87, v84
	v_add_f32_e32 v84, 1.0, v93
	v_rcp_f32_e32 v80, v80
	v_rcp_f32_e32 v81, v81
	v_rcp_f32_e32 v83, v83
	v_rcp_f32_e32 v93, v84
	v_lshl_add_u64 v[96:97], s[36:37], 0, v[88:89]
	v_pk_mul_f32 v[84:85], v[76:77], v[80:81]
	v_pk_mul_f32 v[80:81], v[72:73], v[82:83]
	v_pk_mul_f32 v[86:87], v[78:79], v[86:87]
	v_pk_mul_f32 v[82:83], v[74:75], v[92:93]
	v_cvt_pk_bf16_f32 v92, v84, v85
	v_cvt_pk_bf16_f32 v93, v86, v87
	v_lshl_add_u64 v[96:97], v[156:157], 1, v[96:97]
	v_cmp_gt_u64_e32 vcc, s[20:21], v[90:91]
	v_cvt_pk_bf16_f32 v94, v80, v81
	v_cvt_pk_bf16_f32 v95, v82, v83
	global_store_dwordx4 v[96:97], v[92:95], off nt
	s_and_saveexec_b64 s[26:27], vcc
	s_xor_b64 s[26:27], exec, s[26:27]
	s_cbranch_execz .LBB0_420
	v_and_b32_e32 v91, 0x3fff, v90
	v_cmp_lt_u32_e32 vcc, s78, v91
	v_mov_b64_e32 v[92:93], 0
	s_and_saveexec_b64 s[28:29], vcc
	v_lshrrev_b32_e32 v90, 14, v90
	v_mul_u32_u24_e32 v90, 30, v90
	v_add3_u32 v144, v91, v90, s79
	v_lshlrev_b64 v[90:91], 11, v[144:145]
	v_lshl_add_u64 v[90:91], s[6:7], 0, v[90:91]
	v_lshl_add_u64 v[92:93], v[156:157], 2, v[90:91]
	s_or_b64 exec, exec, s[28:29]
	s_andn2_saveexec_b64 s[26:27], s[26:27]
	s_cbranch_execnz .LBB0_421

;     __device__ __forceinline__ void conv_piece(size_t row, int ch, f32x4 v0, f32x4 v1, const f32x4 g0, const f32x4 g1) const {
;     ...
;         if (dst) { *(f32x4*)dst = v0; *(f32x4*)(dst + 4) = v1; }
.LBB0_367:
	global_store_dwordx4 v[92:93], v[84:87], off nt
	global_store_dwordx4 v[92:93], v[80:83], off offset:16 nt

; #define LAS __attribute__((address_space(3)))
; __device__ __forceinline__ float sigmoidf_(float x) { return __builtin_amdgcn_rcpf(1.f + __builtin_amdgcn_exp2f(-1.4426950408889634f * x)); }
; #define EPI_FOR_ROWS for (int ai = 0; ai < 2; ++ai) _Pragma("unroll") for (int m = 0; m < 4; ++m)
; __device__ __forceinline__ u32x4 pack8(const f32x4 a, const f32x4 b) { u32x4 w; w.x = cvt_pk_bf16(a[0], a[1]); w.y = cvt_pk_bf16(a[2], a[3]); w.z = cvt_pk_bf16(b[0], b[1]); w.w = cvt_pk_bf16(b[2], b[3]); return w; }
;     __device__ __forceinline__ void conv_piece(size_t row, int ch, f32x4 v0, f32x4 v1, const f32x4 g0, const f32x4 g1) const {
; #pragma unroll
;         for (int e = 0; e < 4; ++e) { v0[e] *= sigmoidf_(g0[e]); v1[e] *= sigmoidf_(g1[e]); }
;         *(u32x4*)(Vb + row * DCONV + ch) = pack8(v0, v1);
;         float* dst = nullptr;
;         if (row >= (size_t)NP) { const int r = (int)row - NP; dst = out + O_CVS + (size_t)((r >> 4) * 30 + 14 + (r & 15)) * DCONV + ch; }
;         else { const int t = (int)row & (SEQ - 1); if (t >= SEQ - 30) dst = out + O_CVP + (size_t)(((int)row >> 14) * 30 + (t - (SEQ - 30))) * DCONV + ch; }
;         if (dst) { *(f32x4*)dst = v0; *(f32x4*)(dst + 4) = v1; }
;     }
;     __device__ __forceinline__ void small(size_t row, int col, const f32x4 v0, const f32x4 v1) const { *(u32x4*)(Ub + row * DSSM + col) = pack8(v0, v1); }
;     __device__ __forceinline__ void operator()(const f32x4 (&acc)[2][2][4][2], const Unit& u, int wr, int wc, int fr_, int fq_, LAS unsigned char*) const {
;         int fr = fr_, fq = fq_; asm volatile("" : "+v"(fr), "+v"(fq));
;         const int pn = u.aux;
; #pragma unroll
;         EPI_FOR_ROWS {
;             const int rl = ai * HALF + wr * 64 + m * 16 + fr; const size_t row = (size_t)u.row0 + rl;
;             if (pn < 2) {
; #pragma unroll
;                 for (int bj = 0; bj < 2; ++bj) *(u32x4*)(Ub + row * DSSM + pn * 256 + bj * HALF + wc * 32 + 8 * fq) = pack8(acc[ai][bj][m][0], acc[ai][bj][m][1]);
;             } else {
;                 conv_piece(row, (pn - 2) * 128 + wc * 32 + 8 * fq, acc[ai][0][m][0], acc[ai][0][m][1], acc[ai][1][m][0], acc[ai][1][m][1]);
.LBB0_369:
	s_and_b64 vcc, exec, s[26:27]
	s_cbranch_vccz .LBB0_371
	v_cvt_pk_bf16_f32 v76, v76, v77
	v_cvt_pk_bf16_f32 v77, v78, v79
	v_cvt_pk_bf16_f32 v78, v72, v73
	v_lshl_add_u64 v[72:73], s[60:61], 0, v[88:89]
	v_lshl_add_u64 v[72:73], s[62:63], 1, v[72:73]
	s_lshl_b32 s10, s71, 1
	v_lshl_add_u64 v[72:73], v[72:73], 0, s[10:11]
	v_lshl_add_u64 v[72:73], v[154:155], 1, v[72:73]
	v_cvt_pk_bf16_f32 v79, v74, v75
	global_store_dwordx4 v[72:73], v[76:79], off nt
	v_cvt_pk_bf16_f32 v68, v68, v69
	v_cvt_pk_bf16_f32 v69, v70, v71
	v_cvt_pk_bf16_f32 v70, v64, v65
	v_cvt_pk_bf16_f32 v71, v66, v67
	global_store_dwordx4 v[72:73], v[68:71], off offset:256 nt
.LBB0_371:
	v_add_u32_e32 v64, 0x80, v158
	v_ashrrev_i32_e32 v65, 31, v64
	v_lshl_add_u64 v[74:75], v[64:65], 0, s[16:17]
	s_mov_b64 s[26:27], -1
	s_and_b64 vcc, exec, s[4:5]
	v_lshlrev_b64 v[72:73], 10, v[74:75]
	s_cbranch_vccnz .LBB0_379
	v_mul_f32_e32 v65, 0xbfb8aa3b, v48
	v_mul_f32_e32 v66, 0xbfb8aa3b, v53
	v_exp_f32_e32 v65, v65
	v_exp_f32_e32 v67, v66
	v_mul_f32_e32 v66, 0xbfb8aa3b, v49
	v_exp_f32_e32 v68, v66
	v_add_f32_e32 v65, 1.0, v65
	v_rcp_f32_e32 v66, v65
	v_add_f32_e32 v65, 1.0, v67
	v_add_f32_e32 v67, 1.0, v68
	v_mul_f32_e32 v68, 0xbfb8aa3b, v54
	v_exp_f32_e32 v68, v68
	v_mul_f32_e32 v69, 0xbfb8aa3b, v50
	v_exp_f32_e32 v69, v69
	v_mul_f32_e32 v64, 0xbfb8aa3b, v52
	v_add_f32_e32 v68, 1.0, v68
	v_rcp_f32_e32 v70, v68
	v_add_f32_e32 v68, 1.0, v69
	v_mul_f32_e32 v69, 0xbfb8aa3b, v55
	v_exp_f32_e32 v69, v69
	v_mul_f32_e32 v71, 0xbfb8aa3b, v51
	v_exp_f32_e32 v64, v64
	v_exp_f32_e32 v77, v71
	v_rcp_f32_e32 v76, v68
	v_add_f32_e32 v68, 1.0, v69
	v_add_f32_e32 v64, 1.0, v64
	v_rcp_f32_e32 v71, v68
	v_add_f32_e32 v68, 1.0, v77
	v_rcp_f32_e32 v64, v64
	v_rcp_f32_e32 v65, v65
	v_rcp_f32_e32 v67, v67
	v_rcp_f32_e32 v77, v68
	v_lshl_add_u64 v[80:81], s[36:37], 0, v[72:73]
	v_pk_mul_f32 v[68:69], v[60:61], v[64:65]
	v_pk_mul_f32 v[64:65], v[56:57], v[66:67]
	v_pk_mul_f32 v[70:71], v[62:63], v[70:71]
	v_pk_mul_f32 v[66:67], v[58:59], v[76:77]
	v_cvt_pk_bf16_f32 v76, v68, v69
	v_cvt_pk_bf16_f32 v77, v70, v71
	v_lshl_add_u64 v[80:81], v[156:157], 1, v[80:81]
	v_cmp_gt_u64_e32 vcc, s[20:21], v[74:75]
	v_cvt_pk_bf16_f32 v78, v64, v65
	v_cvt_pk_bf16_f32 v79, v66, v67
	global_store_dwordx4 v[80:81], v[76:79], off nt
	s_and_saveexec_b64 s[26:27], vcc
	s_xor_b64 s[26:27], exec, s[26:27]
	s_cbranch_execz .LBB0_422
	v_and_b32_e32 v75, 0x3fff, v74
	v_cmp_lt_u32_e32 vcc, s78, v75
	v_mov_b64_e32 v[76:77], 0
	s_and_saveexec_b64 s[28:29], vcc
	v_lshrrev_b32_e32 v74, 14, v74
	v_mul_u32_u24_e32 v74, 30, v74
	v_add3_u32 v144, v75, v74, s79
	v_lshlrev_b64 v[74:75], 11, v[144:145]
	v_lshl_add_u64 v[74:75], s[6:7], 0, v[74:75]
	v_lshl_add_u64 v[76:77], v[156:157], 2, v[74:75]
	s_or_b64 exec, exec, s[28:29]
	s_andn2_saveexec_b64 s[26:27], s[26:27]
	s_cbranch_execnz .LBB0_423

;     __device__ __forceinline__ void conv_piece(size_t row, int ch, f32x4 v0, f32x4 v1, const f32x4 g0, const f32x4 g1) const {
;     ...
;         if (dst) { *(f32x4*)dst = v0; *(f32x4*)(dst + 4) = v1; }
.LBB0_377:
	global_store_dwordx4 v[76:77], v[68:71], off nt
	global_store_dwordx4 v[76:77], v[64:67], off offset:16 nt

; #define LAS __attribute__((address_space(3)))
; __device__ __forceinline__ float sigmoidf_(float x) { return __builtin_amdgcn_rcpf(1.f + __builtin_amdgcn_exp2f(-1.4426950408889634f * x)); }
; #define EPI_FOR_ROWS for (int ai = 0; ai < 2; ++ai) _Pragma("unroll") for (int m = 0; m < 4; ++m)
; __device__ __forceinline__ u32x4 pack8(const f32x4 a, const f32x4 b) { u32x4 w; w.x = cvt_pk_bf16(a[0], a[1]); w.y = cvt_pk_bf16(a[2], a[3]); w.z = cvt_pk_bf16(b[0], b[1]); w.w = cvt_pk_bf16(b[2], b[3]); return w; }
;     __device__ __forceinline__ void conv_piece(size_t row, int ch, f32x4 v0, f32x4 v1, const f32x4 g0, const f32x4 g1) const {
; #pragma unroll
;         for (int e = 0; e < 4; ++e) { v0[e] *= sigmoidf_(g0[e]); v1[e] *= sigmoidf_(g1[e]); }
;         *(u32x4*)(Vb + row * DCONV + ch) = pack8(v0, v1);
;         float* dst = nullptr;
;         if (row >= (size_t)NP) { const int r = (int)row - NP; dst = out + O_CVS + (size_t)((r >> 4) * 30 + 14 + (r & 15)) * DCONV + ch; }
;         else { const int t = (int)row & (SEQ - 1); if (t >= SEQ - 30) dst = out + O_CVP + (size_t)(((int)row >> 14) * 30 + (t - (SEQ - 30))) * DCONV + ch; }
;         if (dst) { *(f32x4*)dst = v0; *(f32x4*)(dst + 4) = v1; }
;     }
;     __device__ __forceinline__ void small(size_t row, int col, const f32x4 v0, const f32x4 v1) const { *(u32x4*)(Ub + row * DSSM + col) = pack8(v0, v1); }
;     __device__ __forceinline__ void operator()(const f32x4 (&acc)[2][2][4][2], const Unit& u, int wr, int wc, int fr_, int fq_, LAS unsigned char*) const {
;         int fr = fr_, fq = fq_; asm volatile("" : "+v"(fr), "+v"(fq));
;         const int pn = u.aux;
; #pragma unroll
;         EPI_FOR_ROWS {
;             const int rl = ai * HALF + wr * 64 + m * 16 + fr; const size_t row = (size_t)u.row0 + rl;
;             if (pn < 2) {
; #pragma unroll
;                 for (int bj = 0; bj < 2; ++bj) *(u32x4*)(Ub + row * DSSM + pn * 256 + bj * HALF + wc * 32 + 8 * fq) = pack8(acc[ai][bj][m][0], acc[ai][bj][m][1]);
;             } else {
;                 conv_piece(row, (pn - 2) * 128 + wc * 32 + 8 * fq, acc[ai][0][m][0], acc[ai][0][m][1], acc[ai][1][m][0], acc[ai][1][m][1]);
.LBB0_379:
	s_and_b64 vcc, exec, s[26:27]
	s_cbranch_vccz .LBB0_381
	v_cvt_pk_bf16_f32 v60, v60, v61
	v_cvt_pk_bf16_f32 v61, v62, v63
	v_cvt_pk_bf16_f32 v62, v56, v57
	v_lshl_add_u64 v[56:57], s[60:61], 0, v[72:73]
	v_lshl_add_u64 v[56:57], s[62:63], 1, v[56:57]
	s_lshl_b32 s10, s71, 1
	v_lshl_add_u64 v[56:57], v[56:57], 0, s[10:11]
	v_lshl_add_u64 v[56:57], v[154:155], 1, v[56:57]
	v_cvt_pk_bf16_f32 v63, v58, v59
	global_store_dwordx4 v[56:57], v[60:63], off nt
	v_cvt_pk_bf16_f32 v52, v52, v53
	v_cvt_pk_bf16_f32 v53, v54, v55
	v_cvt_pk_bf16_f32 v54, v48, v49
	v_cvt_pk_bf16_f32 v55, v50, v51
	global_store_dwordx4 v[56:57], v[52:55], off offset:256 nt
.LBB0_381:
	v_add_u32_e32 v48, 0x90, v158
	v_ashrrev_i32_e32 v49, 31, v48
	v_lshl_add_u64 v[58:59], v[48:49], 0, s[16:17]
	s_mov_b64 s[26:27], -1
	s_and_b64 vcc, exec, s[4:5]
	v_lshlrev_b64 v[56:57], 10, v[58:59]
	s_cbranch_vccnz .LBB0_389
	v_mul_f32_e32 v49, 0xbfb8aa3b, v32
	v_mul_f32_e32 v50, 0xbfb8aa3b, v37
	v_exp_f32_e32 v49, v49
	v_exp_f32_e32 v51, v50
	v_mul_f32_e32 v50, 0xbfb8aa3b, v33
	v_exp_f32_e32 v52, v50
	v_add_f32_e32 v49, 1.0, v49
	v_rcp_f32_e32 v50, v49
	v_add_f32_e32 v49, 1.0, v51
	v_add_f32_e32 v51, 1.0, v52
	v_mul_f32_e32 v52, 0xbfb8aa3b, v38
	v_exp_f32_e32 v52, v52
	v_mul_f32_e32 v53, 0xbfb8aa3b, v34
	v_exp_f32_e32 v53, v53
	v_mul_f32_e32 v48, 0xbfb8aa3b, v36
	v_add_f32_e32 v52, 1.0, v52
	v_rcp_f32_e32 v54, v52
	v_add_f32_e32 v52, 1.0, v53
	v_mul_f32_e32 v53, 0xbfb8aa3b, v39
	v_exp_f32_e32 v53, v53
	v_mul_f32_e32 v55, 0xbfb8aa3b, v35
	v_exp_f32_e32 v48, v48
	v_exp_f32_e32 v61, v55
	v_rcp_f32_e32 v60, v52
	v_add_f32_e32 v52, 1.0, v53
	v_add_f32_e32 v48, 1.0, v48
	v_rcp_f32_e32 v55, v52
	v_add_f32_e32 v52, 1.0, v61
	v_rcp_f32_e32 v48, v48
	v_rcp_f32_e32 v49, v49
	v_rcp_f32_e32 v51, v51
	v_rcp_f32_e32 v61, v52
	v_lshl_add_u64 v[64:65], s[36:37], 0, v[56:57]
	v_pk_mul_f32 v[52:53], v[44:45], v[48:49]
	v_pk_mul_f32 v[48:49], v[40:41], v[50:51]
	v_pk_mul_f32 v[54:55], v[46:47], v[54:55]
	v_pk_mul_f32 v[50:51], v[42:43], v[60:61]
	v_cvt_pk_bf16_f32 v60, v52, v53
	v_cvt_pk_bf16_f32 v61, v54, v55
	v_lshl_add_u64 v[64:65], v[156:157], 1, v[64:65]
	v_cmp_gt_u64_e32 vcc, s[20:21], v[58:59]
	v_cvt_pk_bf16_f32 v62, v48, v49
	v_cvt_pk_bf16_f32 v63, v50, v51
	global_store_dwordx4 v[64:65], v[60:63], off nt
	s_and_saveexec_b64 s[26:27], vcc
	s_xor_b64 s[26:27], exec, s[26:27]
	s_cbranch_execz .LBB0_424
	v_and_b32_e32 v59, 0x3fff, v58
	v_cmp_lt_u32_e32 vcc, s78, v59
	v_mov_b64_e32 v[60:61], 0
	s_and_saveexec_b64 s[28:29], vcc
	v_lshrrev_b32_e32 v58, 14, v58
	v_mul_u32_u24_e32 v58, 30, v58
	v_add3_u32 v144, v59, v58, s79
	v_lshlrev_b64 v[58:59], 11, v[144:145]
	v_lshl_add_u64 v[58:59], s[6:7], 0, v[58:59]
	v_lshl_add_u64 v[60:61], v[156:157], 2, v[58:59]
	s_or_b64 exec, exec, s[28:29]
	s_andn2_saveexec_b64 s[26:27], s[26:27]
	s_cbranch_execnz .LBB0_425

;     __device__ __forceinline__ void conv_piece(size_t row, int ch, f32x4 v0, f32x4 v1, const f32x4 g0, const f32x4 g1) const {
;     ...
;         if (row >= (size_t)NP) { const int r = (int)row - NP; dst = out + O_CVS + (size_t)((r >> 4) * 30 + 14 + (r & 15)) * DCONV + ch; }
;         else { const int t = (int)row & (SEQ - 1); if (t >= SEQ - 30) dst = out + O_CVP + (size_t)(((int)row >> 14) * 30 + (t - (SEQ - 30))) * DCONV + ch; }
;         if (dst) { *(f32x4*)dst = v0; *(f32x4*)(dst + 4) = v1; }
.LBB0_387:
	global_store_dwordx4 v[60:61], v[52:55], off nt
	global_store_dwordx4 v[60:61], v[48:51], off offset:16 nt

; #define LAS __attribute__((address_space(3)))
; __device__ __forceinline__ float sigmoidf_(float x) { return __builtin_amdgcn_rcpf(1.f + __builtin_amdgcn_exp2f(-1.4426950408889634f * x)); }
; #define EPI_FOR_ROWS for (int ai = 0; ai < 2; ++ai) _Pragma("unroll") for (int m = 0; m < 4; ++m)
; __device__ __forceinline__ u32x4 pack8(const f32x4 a, const f32x4 b) { u32x4 w; w.x = cvt_pk_bf16(a[0], a[1]); w.y = cvt_pk_bf16(a[2], a[3]); w.z = cvt_pk_bf16(b[0], b[1]); w.w = cvt_pk_bf16(b[2], b[3]); return w; }
;     __device__ __forceinline__ void conv_piece(size_t row, int ch, f32x4 v0, f32x4 v1, const f32x4 g0, const f32x4 g1) const {
; #pragma unroll
;         for (int e = 0; e < 4; ++e) { v0[e] *= sigmoidf_(g0[e]); v1[e] *= sigmoidf_(g1[e]); }
;         *(u32x4*)(Vb + row * DCONV + ch) = pack8(v0, v1);
;         float* dst = nullptr;
;         if (row >= (size_t)NP) { const int r = (int)row - NP; dst = out + O_CVS + (size_t)((r >> 4) * 30 + 14 + (r & 15)) * DCONV + ch; }
;         else { const int t = (int)row & (SEQ - 1); if (t >= SEQ - 30) dst = out + O_CVP + (size_t)(((int)row >> 14) * 30 + (t - (SEQ - 30))) * DCONV + ch; }
;         if (dst) { *(f32x4*)dst = v0; *(f32x4*)(dst + 4) = v1; }
;     }
;     __device__ __forceinline__ void small(size_t row, int col, const f32x4 v0, const f32x4 v1) const { *(u32x4*)(Ub + row * DSSM + col) = pack8(v0, v1); }
;     __device__ __forceinline__ void operator()(const f32x4 (&acc)[2][2][4][2], const Unit& u, int wr, int wc, int fr_, int fq_, LAS unsigned char*) const {
;         int fr = fr_, fq = fq_; asm volatile("" : "+v"(fr), "+v"(fq));
;         const int pn = u.aux;
; #pragma unroll
;         EPI_FOR_ROWS {
;             const int rl = ai * HALF + wr * 64 + m * 16 + fr; const size_t row = (size_t)u.row0 + rl;
;             if (pn < 2) {
; #pragma unroll
;                 for (int bj = 0; bj < 2; ++bj) *(u32x4*)(Ub + row * DSSM + pn * 256 + bj * HALF + wc * 32 + 8 * fq) = pack8(acc[ai][bj][m][0], acc[ai][bj][m][1]);
;             } else {
;                 conv_piece(row, (pn - 2) * 128 + wc * 32 + 8 * fq, acc[ai][0][m][0], acc[ai][0][m][1], acc[ai][1][m][0], acc[ai][1][m][1]);
.LBB0_389:
	s_and_b64 vcc, exec, s[26:27]
	s_cbranch_vccz .LBB0_391
	v_cvt_pk_bf16_f32 v44, v44, v45
	v_cvt_pk_bf16_f32 v45, v46, v47
	v_cvt_pk_bf16_f32 v46, v40, v41
	v_lshl_add_u64 v[40:41], s[60:61], 0, v[56:57]
	v_lshl_add_u64 v[40:41], s[62:63], 1, v[40:41]
	s_lshl_b32 s10, s71, 1
	v_lshl_add_u64 v[40:41], v[40:41], 0, s[10:11]
	v_lshl_add_u64 v[40:41], v[154:155], 1, v[40:41]
	v_cvt_pk_bf16_f32 v47, v42, v43
	global_store_dwordx4 v[40:41], v[44:47], off nt
	v_cvt_pk_bf16_f32 v36, v36, v37
	v_cvt_pk_bf16_f32 v37, v38, v39
	v_cvt_pk_bf16_f32 v38, v32, v33
	v_cvt_pk_bf16_f32 v39, v34, v35
	global_store_dwordx4 v[40:41], v[36:39], off offset:256 nt
.LBB0_391:
	v_add_u32_e32 v32, 0xa0, v158
	v_ashrrev_i32_e32 v33, 31, v32
	v_lshl_add_u64 v[42:43], v[32:33], 0, s[16:17]
	s_mov_b64 s[26:27], -1
	s_and_b64 vcc, exec, s[4:5]
	v_lshlrev_b64 v[40:41], 10, v[42:43]
	s_cbranch_vccnz .LBB0_399
	v_mul_f32_e32 v33, 0xbfb8aa3b, v16
	v_mul_f32_e32 v34, 0xbfb8aa3b, v21
	v_exp_f32_e32 v33, v33
	v_exp_f32_e32 v35, v34
	v_mul_f32_e32 v34, 0xbfb8aa3b, v17
	v_exp_f32_e32 v36, v34
	v_add_f32_e32 v33, 1.0, v33
	v_rcp_f32_e32 v34, v33
	v_add_f32_e32 v33, 1.0, v35
	v_add_f32_e32 v35, 1.0, v36
	v_mul_f32_e32 v36, 0xbfb8aa3b, v22
	v_exp_f32_e32 v36, v36
	v_mul_f32_e32 v37, 0xbfb8aa3b, v18
	v_exp_f32_e32 v37, v37
	v_mul_f32_e32 v32, 0xbfb8aa3b, v20
	v_add_f32_e32 v36, 1.0, v36
	v_rcp_f32_e32 v38, v36
	v_add_f32_e32 v36, 1.0, v37
	v_mul_f32_e32 v37, 0xbfb8aa3b, v23
	v_exp_f32_e32 v37, v37
	v_mul_f32_e32 v39, 0xbfb8aa3b, v19
	v_exp_f32_e32 v32, v32
	v_exp_f32_e32 v45, v39
	v_rcp_f32_e32 v44, v36
	v_add_f32_e32 v36, 1.0, v37
	v_add_f32_e32 v32, 1.0, v32
	v_rcp_f32_e32 v39, v36
	v_add_f32_e32 v36, 1.0, v45
	v_rcp_f32_e32 v32, v32
	v_rcp_f32_e32 v33, v33
	v_rcp_f32_e32 v35, v35
	v_rcp_f32_e32 v45, v36
	v_lshl_add_u64 v[48:49], s[36:37], 0, v[40:41]
	v_pk_mul_f32 v[36:37], v[28:29], v[32:33]
	v_pk_mul_f32 v[32:33], v[24:25], v[34:35]
	v_pk_mul_f32 v[38:39], v[30:31], v[38:39]
	v_pk_mul_f32 v[34:35], v[26:27], v[44:45]
	v_cvt_pk_bf16_f32 v44, v36, v37
	v_cvt_pk_bf16_f32 v45, v38, v39
	v_lshl_add_u64 v[48:49], v[156:157], 1, v[48:49]
	v_cmp_gt_u64_e32 vcc, s[20:21], v[42:43]
	v_cvt_pk_bf16_f32 v46, v32, v33
	v_cvt_pk_bf16_f32 v47, v34, v35
	global_store_dwordx4 v[48:49], v[44:47], off nt
	s_and_saveexec_b64 s[26:27], vcc
	s_xor_b64 s[26:27], exec, s[26:27]
	s_cbranch_execz .LBB0_426
	v_and_b32_e32 v43, 0x3fff, v42
	v_cmp_lt_u32_e32 vcc, s78, v43
	v_mov_b64_e32 v[44:45], 0
	s_and_saveexec_b64 s[28:29], vcc
	v_lshrrev_b32_e32 v42, 14, v42
	v_mul_u32_u24_e32 v42, 30, v42
	v_add3_u32 v144, v43, v42, s79
	v_lshlrev_b64 v[42:43], 11, v[144:145]
	v_lshl_add_u64 v[42:43], s[6:7], 0, v[42:43]
	v_lshl_add_u64 v[44:45], v[156:157], 2, v[42:43]
	s_or_b64 exec, exec, s[28:29]
	s_andn2_saveexec_b64 s[26:27], s[26:27]
	s_cbranch_execnz .LBB0_427

;     __device__ __forceinline__ void conv_piece(size_t row, int ch, f32x4 v0, f32x4 v1, const f32x4 g0, const f32x4 g1) const {
;     ...
;         if (row >= (size_t)NP) { const int r = (int)row - NP; dst = out + O_CVS + (size_t)((r >> 4) * 30 + 14 + (r & 15)) * DCONV + ch; }
;         else { const int t = (int)row & (SEQ - 1); if (t >= SEQ - 30) dst = out + O_CVP + (size_t)(((int)row >> 14) * 30 + (t - (SEQ - 30))) * DCONV + ch; }
;         if (dst) { *(f32x4*)dst = v0; *(f32x4*)(dst + 4) = v1; }
.LBB0_397:
	global_store_dwordx4 v[44:45], v[36:39], off nt
	global_store_dwordx4 v[44:45], v[32:35], off offset:16 nt

; #define LAS __attribute__((address_space(3)))
; __device__ __forceinline__ float sigmoidf_(float x) { return __builtin_amdgcn_rcpf(1.f + __builtin_amdgcn_exp2f(-1.4426950408889634f * x)); }
; #define EPI_FOR_ROWS for (int ai = 0; ai < 2; ++ai) _Pragma("unroll") for (int m = 0; m < 4; ++m)
; __device__ __forceinline__ u32x4 pack8(const f32x4 a, const f32x4 b) { u32x4 w; w.x = cvt_pk_bf16(a[0], a[1]); w.y = cvt_pk_bf16(a[2], a[3]); w.z = cvt_pk_bf16(b[0], b[1]); w.w = cvt_pk_bf16(b[2], b[3]); return w; }
;     __device__ __forceinline__ void conv_piece(size_t row, int ch, f32x4 v0, f32x4 v1, const f32x4 g0, const f32x4 g1) const {
; #pragma unroll
;         for (int e = 0; e < 4; ++e) { v0[e] *= sigmoidf_(g0[e]); v1[e] *= sigmoidf_(g1[e]); }
;         *(u32x4*)(Vb + row * DCONV + ch) = pack8(v0, v1);
;         float* dst = nullptr;
;         if (row >= (size_t)NP) { const int r = (int)row - NP; dst = out + O_CVS + (size_t)((r >> 4) * 30 + 14 + (r & 15)) * DCONV + ch; }
;         else { const int t = (int)row & (SEQ - 1); if (t >= SEQ - 30) dst = out + O_CVP + (size_t)(((int)row >> 14) * 30 + (t - (SEQ - 30))) * DCONV + ch; }
;         if (dst) { *(f32x4*)dst = v0; *(f32x4*)(dst + 4) = v1; }
;     }
;     __device__ __forceinline__ void small(size_t row, int col, const f32x4 v0, const f32x4 v1) const { *(u32x4*)(Ub + row * DSSM + col) = pack8(v0, v1); }
;     __device__ __forceinline__ void operator()(const f32x4 (&acc)[2][2][4][2], const Unit& u, int wr, int wc, int fr_, int fq_, LAS unsigned char*) const {
;         int fr = fr_, fq = fq_; asm volatile("" : "+v"(fr), "+v"(fq));
;         const int pn = u.aux;
; #pragma unroll
;         EPI_FOR_ROWS {
;             const int rl = ai * HALF + wr * 64 + m * 16 + fr; const size_t row = (size_t)u.row0 + rl;
;             if (pn < 2) {
; #pragma unroll
;                 for (int bj = 0; bj < 2; ++bj) *(u32x4*)(Ub + row * DSSM + pn * 256 + bj * HALF + wc * 32 + 8 * fq) = pack8(acc[ai][bj][m][0], acc[ai][bj][m][1]);
;             } else {
;                 conv_piece(row, (pn - 2) * 128 + wc * 32 + 8 * fq, acc[ai][0][m][0], acc[ai][0][m][1], acc[ai][1][m][0], acc[ai][1][m][1]);
.LBB0_399:
	s_and_b64 vcc, exec, s[26:27]
	s_cbranch_vccz .LBB0_401
	v_cvt_pk_bf16_f32 v28, v28, v29
	v_cvt_pk_bf16_f32 v29, v30, v31
	v_cvt_pk_bf16_f32 v30, v24, v25
	v_lshl_add_u64 v[24:25], s[60:61], 0, v[40:41]
	v_lshl_add_u64 v[24:25], s[62:63], 1, v[24:25]
	s_lshl_b32 s10, s71, 1
	v_lshl_add_u64 v[24:25], v[24:25], 0, s[10:11]
	v_lshl_add_u64 v[24:25], v[154:155], 1, v[24:25]
	v_cvt_pk_bf16_f32 v31, v26, v27
	global_store_dwordx4 v[24:25], v[28:31], off nt
	v_cvt_pk_bf16_f32 v20, v20, v21
	v_cvt_pk_bf16_f32 v21, v22, v23
	v_cvt_pk_bf16_f32 v22, v16, v17
	v_cvt_pk_bf16_f32 v23, v18, v19
	global_store_dwordx4 v[24:25], v[20:23], off offset:256 nt
.LBB0_401:
	v_add_u32_e32 v16, 0xb0, v158
	v_ashrrev_i32_e32 v17, 31, v16
	v_lshl_add_u64 v[26:27], v[16:17], 0, s[16:17]
	s_mov_b64 s[16:17], -1
	s_and_b64 vcc, exec, s[4:5]
	v_lshlrev_b64 v[24:25], 10, v[26:27]
	s_cbranch_vccnz .LBB0_410
	v_mul_f32_e32 v17, 0xbfb8aa3b, v0
	v_mul_f32_e32 v18, 0xbfb8aa3b, v5
	v_exp_f32_e32 v17, v17
	v_exp_f32_e32 v19, v18
	v_mul_f32_e32 v18, 0xbfb8aa3b, v1
	v_exp_f32_e32 v20, v18
	v_add_f32_e32 v17, 1.0, v17
	v_rcp_f32_e32 v18, v17
	v_add_f32_e32 v17, 1.0, v19
	v_add_f32_e32 v19, 1.0, v20
	v_mul_f32_e32 v20, 0xbfb8aa3b, v6
	v_exp_f32_e32 v20, v20
	v_mul_f32_e32 v21, 0xbfb8aa3b, v2
	v_exp_f32_e32 v21, v21
	v_mul_f32_e32 v16, 0xbfb8aa3b, v4
	v_add_f32_e32 v20, 1.0, v20
	v_rcp_f32_e32 v22, v20
	v_add_f32_e32 v20, 1.0, v21
	v_mul_f32_e32 v21, 0xbfb8aa3b, v7
	v_exp_f32_e32 v21, v21
	v_mul_f32_e32 v23, 0xbfb8aa3b, v3
	v_exp_f32_e32 v16, v16
	v_exp_f32_e32 v29, v23
	v_rcp_f32_e32 v28, v20
	v_add_f32_e32 v20, 1.0, v21
	v_add_f32_e32 v16, 1.0, v16
	v_rcp_f32_e32 v23, v20
	v_add_f32_e32 v20, 1.0, v29
	v_rcp_f32_e32 v16, v16
	v_rcp_f32_e32 v17, v17
	v_rcp_f32_e32 v19, v19
	v_rcp_f32_e32 v29, v20
	v_lshl_add_u64 v[32:33], s[36:37], 0, v[24:25]
	v_pk_mul_f32 v[20:21], v[12:13], v[16:17]
	v_pk_mul_f32 v[16:17], v[8:9], v[18:19]
	v_pk_mul_f32 v[22:23], v[14:15], v[22:23]
	v_pk_mul_f32 v[18:19], v[10:11], v[28:29]
	v_cvt_pk_bf16_f32 v28, v20, v21
	v_cvt_pk_bf16_f32 v29, v22, v23
	v_lshl_add_u64 v[32:33], v[156:157], 1, v[32:33]
	v_cmp_gt_u64_e32 vcc, s[20:21], v[26:27]
	v_cvt_pk_bf16_f32 v30, v16, v17
	v_cvt_pk_bf16_f32 v31, v18, v19
	global_store_dwordx4 v[32:33], v[28:31], off nt
	s_and_saveexec_b64 s[4:5], vcc
	s_xor_b64 s[4:5], exec, s[4:5]
	s_cbranch_execz .LBB0_428
	v_and_b32_e32 v27, 0x3fff, v26
	v_cmp_lt_u32_e32 vcc, s78, v27
	v_mov_b64_e32 v[28:29], 0
	s_and_saveexec_b64 s[16:17], vcc
	v_lshrrev_b32_e32 v26, 14, v26
	v_mul_u32_u24_e32 v26, 30, v26
	v_add3_u32 v144, v27, v26, s79
	v_lshlrev_b64 v[26:27], 11, v[144:145]
	v_lshl_add_u64 v[26:27], s[6:7], 0, v[26:27]
	v_lshl_add_u64 v[28:29], v[156:157], 2, v[26:27]
	s_or_b64 exec, exec, s[16:17]
	s_andn2_saveexec_b64 s[4:5], s[4:5]
	s_cbranch_execnz .LBB0_429

;     __device__ __forceinline__ void conv_piece(size_t row, int ch, f32x4 v0, f32x4 v1, const f32x4 g0, const f32x4 g1) const {
;     ...
;         if (row >= (size_t)NP) { const int r = (int)row - NP; dst = out + O_CVS + (size_t)((r >> 4) * 30 + 14 + (r & 15)) * DCONV + ch; }
;         else { const int t = (int)row & (SEQ - 1); if (t >= SEQ - 30) dst = out + O_CVP + (size_t)(((int)row >> 14) * 30 + (t - (SEQ - 30))) * DCONV + ch; }
;         if (dst) { *(f32x4*)dst = v0; *(f32x4*)(dst + 4) = v1; }
.LBB0_407:
	global_store_dwordx4 v[28:29], v[20:23], off nt
	global_store_dwordx4 v[28:29], v[16:19], off offset:16 nt

; __device__ __forceinline__ u32x4 pack8(const f32x4 a, const f32x4 b) { u32x4 w; w.x = cvt_pk_bf16(a[0], a[1]); w.y = cvt_pk_bf16(a[2], a[3]); w.z = cvt_pk_bf16(b[0], b[1]); w.w = cvt_pk_bf16(b[2], b[3]); return w; }
;     __device__ __forceinline__ void operator()(const f32x4 (&acc)[2][2][4][2], const Unit& u, int wr, int wc, int fr_, int fq_, LAS unsigned char*) const {
;     ...
;             if (pn < 2) {
; #pragma unroll
;                 for (int bj = 0; bj < 2; ++bj) *(u32x4*)(Ub + row * DSSM + pn * 256 + bj * HALF + wc * 32 + 8 * fq) = pack8(acc[ai][bj][m][0], acc[ai][bj][m][1]);
.LBB0_410:
	s_and_b64 vcc, exec, s[16:17]
	s_cbranch_vccz .LBB0_409
	v_cvt_pk_bf16_f32 v12, v12, v13
	v_cvt_pk_bf16_f32 v13, v14, v15
	v_cvt_pk_bf16_f32 v14, v8, v9
	v_lshl_add_u64 v[8:9], s[60:61], 0, v[24:25]
	v_lshl_add_u64 v[8:9], s[62:63], 1, v[8:9]
	s_lshl_b32 s10, s71, 1
	v_lshl_add_u64 v[8:9], v[8:9], 0, s[10:11]
	v_lshl_add_u64 v[8:9], v[154:155], 1, v[8:9]
	v_cvt_pk_bf16_f32 v15, v10, v11
	global_store_dwordx4 v[8:9], v[12:15], off nt
	v_cvt_pk_bf16_f32 v4, v4, v5
	v_cvt_pk_bf16_f32 v5, v6, v7
	v_cvt_pk_bf16_f32 v6, v0, v1
	v_cvt_pk_bf16_f32 v7, v2, v3
	global_store_dwordx4 v[8:9], v[4:7], off offset:256 nt
	s_andn2_b64 vcc, exec, s[0:1]
	s_mov_b64 s[0:1], -1
	s_cbranch_vccnz .LBB0_324
